# depthwise conv: the 15 later row loads of each thread issued up front into private registers instead of serialised behind each step's store
# speedup vs baseline: 1.0062x; 1.0027x over previous
.LBB0_650:
	s_or_b64 exec, exec, s[4:5]
	v_lshl_add_u64 v[44:45], s[0:1], 0, v[128:129]
	v_lshlrev_b64 v[70:71], 13, v[40:41]
	v_lshl_add_u64 v[70:71], v[44:45], 0, v[70:71]
	global_load_dwordx4 v[70:73], v[70:71], off
	v_or_b32_e32 v168, 1, v40
	v_ashrrev_i32_e32 v169, 31, v168
	v_lshlrev_b64 v[168:169], 13, v[168:169]
	v_lshl_add_u64 v[168:169], v[44:45], 0, v[168:169]
	global_load_dwordx4 v[92:95], v[168:169], off
	v_or_b32_e32 v168, 2, v40
	v_ashrrev_i32_e32 v169, 31, v168
	v_lshlrev_b64 v[168:169], 13, v[168:169]
	v_lshl_add_u64 v[168:169], v[44:45], 0, v[168:169]
	global_load_dwordx4 v[96:99], v[168:169], off
	v_or_b32_e32 v168, 3, v40
	v_ashrrev_i32_e32 v169, 31, v168
	v_lshlrev_b64 v[168:169], 13, v[168:169]
	v_lshl_add_u64 v[168:169], v[44:45], 0, v[168:169]
	global_load_dwordx4 v[100:103], v[168:169], off
	v_or_b32_e32 v168, 4, v40
	v_ashrrev_i32_e32 v169, 31, v168
	v_lshlrev_b64 v[168:169], 13, v[168:169]
	v_lshl_add_u64 v[168:169], v[44:45], 0, v[168:169]
	global_load_dwordx4 v[104:107], v[168:169], off
	v_or_b32_e32 v168, 5, v40
	v_ashrrev_i32_e32 v169, 31, v168
	v_lshlrev_b64 v[168:169], 13, v[168:169]
	v_lshl_add_u64 v[168:169], v[44:45], 0, v[168:169]
	global_load_dwordx4 v[108:111], v[168:169], off
	v_or_b32_e32 v168, 6, v40
	v_ashrrev_i32_e32 v169, 31, v168
	v_lshlrev_b64 v[168:169], 13, v[168:169]
	v_lshl_add_u64 v[168:169], v[44:45], 0, v[168:169]
	global_load_dwordx4 v[112:115], v[168:169], off
	v_or_b32_e32 v168, 7, v40
	v_ashrrev_i32_e32 v169, 31, v168
	v_lshlrev_b64 v[168:169], 13, v[168:169]
	v_lshl_add_u64 v[168:169], v[44:45], 0, v[168:169]
	global_load_dwordx4 v[116:119], v[168:169], off
	v_or_b32_e32 v168, 8, v40
	v_ashrrev_i32_e32 v169, 31, v168
	v_lshlrev_b64 v[168:169], 13, v[168:169]
	v_lshl_add_u64 v[168:169], v[44:45], 0, v[168:169]
	global_load_dwordx4 v[120:123], v[168:169], off
	v_or_b32_e32 v168, 9, v40
	v_ashrrev_i32_e32 v169, 31, v168
	v_lshlrev_b64 v[168:169], 13, v[168:169]
	v_lshl_add_u64 v[168:169], v[44:45], 0, v[168:169]
	global_load_dwordx4 v[124:127], v[168:169], off
	v_or_b32_e32 v168, 10, v40
	v_ashrrev_i32_e32 v169, 31, v168
	v_lshlrev_b64 v[168:169], 13, v[168:169]
	v_lshl_add_u64 v[168:169], v[44:45], 0, v[168:169]
	global_load_dwordx4 v[136:139], v[168:169], off
	v_or_b32_e32 v168, 11, v40
	v_ashrrev_i32_e32 v169, 31, v168
	v_lshlrev_b64 v[168:169], 13, v[168:169]
	v_lshl_add_u64 v[168:169], v[44:45], 0, v[168:169]
	global_load_dwordx4 v[144:147], v[168:169], off
	v_or_b32_e32 v168, 12, v40
	v_ashrrev_i32_e32 v169, 31, v168
	v_lshlrev_b64 v[168:169], 13, v[168:169]
	v_lshl_add_u64 v[168:169], v[44:45], 0, v[168:169]
	global_load_dwordx4 v[148:151], v[168:169], off
	v_or_b32_e32 v168, 13, v40
	v_ashrrev_i32_e32 v169, 31, v168
	v_lshlrev_b64 v[168:169], 13, v[168:169]
	v_lshl_add_u64 v[168:169], v[44:45], 0, v[168:169]
	global_load_dwordx4 v[152:155], v[168:169], off
	v_or_b32_e32 v168, 14, v40
	v_ashrrev_i32_e32 v169, 31, v168
	v_lshlrev_b64 v[168:169], 13, v[168:169]
	v_lshl_add_u64 v[168:169], v[44:45], 0, v[168:169]
	global_load_dwordx4 v[156:159], v[168:169], off
	v_or_b32_e32 v168, 15, v40
	v_ashrrev_i32_e32 v169, 31, v168
	v_lshlrev_b64 v[168:169], 13, v[168:169]
	v_lshl_add_u64 v[168:169], v[44:45], 0, v[168:169]
	global_load_dwordx4 v[160:163], v[168:169], off
	s_waitcnt vmcnt(22)
	v_pk_fma_f32 v[66:67], v[12:13], v[66:67], v[8:9]
	v_pk_fma_f32 v[64:65], v[14:15], v[64:65], v[10:11]
	v_pk_fma_f32 v[62:63], v[4:5], v[62:63], v[0:1]
	v_pk_fma_f32 v[42:43], v[6:7], v[42:43], v[2:3]
	s_add_u32 s0, s88, 0x1fa00000
	s_waitcnt vmcnt(17)
	v_pk_fma_f32 v[66:67], v[36:37], v[60:61], v[66:67]
	v_pk_fma_f32 v[64:65], v[38:39], v[58:59], v[64:65]
	v_pk_fma_f32 v[62:63], v[24:25], v[56:57], v[62:63]
	v_pk_fma_f32 v[78:79], v[26:27], v[54:55], v[42:43]
	v_or_b32_e32 v76, 1, v40
	s_addc_u32 s1, s89, 0
	v_pk_fma_f32 v[66:67], v[32:33], v[52:53], v[66:67]
	v_pk_fma_f32 v[64:65], v[34:35], v[50:51], v[64:65]
	v_pk_fma_f32 v[62:63], v[28:29], v[48:49], v[62:63]
	v_pk_fma_f32 v[78:79], v[30:31], v[46:47], v[78:79]
	v_lshlrev_b64 v[74:75], 12, v[40:41]
	v_ashrrev_i32_e32 v77, 31, v76
	v_lshl_add_u64 v[42:43], s[0:1], 0, v[128:129]
	v_lshlrev_b64 v[80:81], 13, v[76:77]
	v_lshl_add_u64 v[74:75], v[42:43], 0, v[74:75]
	v_lshl_add_u64 v[80:81], v[44:45], 0, v[80:81]
	v_pk_fma_f32 v[60:61], v[12:13], v[60:61], v[8:9]
	v_pk_fma_f32 v[58:59], v[14:15], v[58:59], v[10:11]
	v_pk_fma_f32 v[56:57], v[4:5], v[56:57], v[0:1]
	v_pk_fma_f32 v[54:55], v[6:7], v[54:55], v[2:3]
	v_pk_fma_f32 v[60:61], v[36:37], v[52:53], v[60:61]
	v_pk_fma_f32 v[58:59], v[38:39], v[50:51], v[58:59]
	v_pk_fma_f32 v[56:57], v[24:25], v[48:49], v[56:57]
	v_pk_fma_f32 v[54:55], v[26:27], v[46:47], v[54:55]
	v_pk_fma_f32 v[52:53], v[12:13], v[52:53], v[8:9]
	v_pk_fma_f32 v[50:51], v[14:15], v[50:51], v[10:11]
	v_pk_fma_f32 v[48:49], v[4:5], v[48:49], v[0:1]
	v_pk_fma_f32 v[46:47], v[6:7], v[46:47], v[2:3]
	s_mov_b32 s34, s12
	s_mov_b32 s36, s2
	s_mov_b32 s14, 0x7fffe0
	v_mov_b32_e32 v135, v129
	v_mov_b32_e32 v131, v129
	v_mov_b32_e32 v133, v129
	s_waitcnt vmcnt(15)
	v_lshlrev_b32_e32 v82, 16, v70
	v_and_b32_e32 v83, 0xffff0000, v70
	v_lshlrev_b32_e32 v70, 16, v71
	v_and_b32_e32 v71, 0xffff0000, v71
	v_lshlrev_b32_e32 v84, 16, v72
	v_and_b32_e32 v85, 0xffff0000, v72
	v_lshlrev_b32_e32 v72, 16, v73
	v_and_b32_e32 v73, 0xffff0000, v73
	v_pk_fma_f32 v[66:67], v[20:21], v[82:83], v[66:67]
	v_pk_fma_f32 v[64:65], v[22:23], v[70:71], v[64:65]
	v_pk_fma_f32 v[86:87], v[16:17], v[84:85], v[62:63]
	v_pk_fma_f32 v[78:79], v[18:19], v[72:73], v[78:79]
	v_cvt_pk_bf16_f32 v62, v66, v67
	v_cvt_pk_bf16_f32 v63, v64, v65
	v_cvt_pk_bf16_f32 v64, v86, v87
	v_cvt_pk_bf16_f32 v65, v78, v79
	global_store_dwordx4 v[74:75], v[62:65], off
	v_or_b32_e32 v66, 2, v40
	v_pk_fma_f32 v[60:61], v[32:33], v[82:83], v[60:61]
	v_pk_fma_f32 v[58:59], v[34:35], v[70:71], v[58:59]
	v_pk_fma_f32 v[56:57], v[28:29], v[84:85], v[56:57]
	v_pk_fma_f32 v[54:55], v[30:31], v[72:73], v[54:55]
	v_ashrrev_i32_e32 v67, 31, v66
	v_lshlrev_b64 v[74:75], 12, v[76:77]
	v_lshlrev_b64 v[76:77], 13, v[66:67]
	v_lshl_add_u64 v[74:75], v[42:43], 0, v[74:75]
	v_lshl_add_u64 v[76:77], v[44:45], 0, v[76:77]
	v_pk_fma_f32 v[52:53], v[36:37], v[82:83], v[52:53]
	v_pk_fma_f32 v[50:51], v[38:39], v[70:71], v[50:51]
	v_pk_fma_f32 v[48:49], v[24:25], v[84:85], v[48:49]
	v_pk_fma_f32 v[46:47], v[26:27], v[72:73], v[46:47]
	v_pk_fma_f32 v[72:73], v[6:7], v[72:73], v[2:3]
	s_waitcnt vmcnt(14)
	v_lshlrev_b32_e32 v78, 16, v92
	v_and_b32_e32 v79, 0xffff0000, v92
	v_lshlrev_b32_e32 v62, 16, v93
	v_and_b32_e32 v63, 0xffff0000, v93
	v_lshlrev_b32_e32 v80, 16, v94
	v_and_b32_e32 v81, 0xffff0000, v94
	v_lshlrev_b32_e32 v64, 16, v95
	v_and_b32_e32 v65, 0xffff0000, v95
	v_pk_fma_f32 v[60:61], v[20:21], v[78:79], v[60:61]
	v_pk_fma_f32 v[58:59], v[22:23], v[62:63], v[58:59]
	v_pk_fma_f32 v[56:57], v[16:17], v[80:81], v[56:57]
	v_pk_fma_f32 v[86:87], v[18:19], v[64:65], v[54:55]
	v_cvt_pk_bf16_f32 v54, v60, v61
	v_cvt_pk_bf16_f32 v55, v58, v59
	v_cvt_pk_bf16_f32 v56, v56, v57
	v_cvt_pk_bf16_f32 v57, v86, v87
	global_store_dwordx4 v[74:75], v[54:57], off
	v_or_b32_e32 v58, 3, v40
	v_pk_fma_f32 v[52:53], v[32:33], v[78:79], v[52:53]
	v_pk_fma_f32 v[50:51], v[34:35], v[62:63], v[50:51]
	v_pk_fma_f32 v[48:49], v[28:29], v[80:81], v[48:49]
	v_pk_fma_f32 v[46:47], v[30:31], v[64:65], v[46:47]
	v_ashrrev_i32_e32 v59, 31, v58
	v_lshlrev_b64 v[60:61], 12, v[66:67]
	v_lshlrev_b64 v[66:67], 13, v[58:59]
	v_lshl_add_u64 v[60:61], v[42:43], 0, v[60:61]
	v_lshl_add_u64 v[66:67], v[44:45], 0, v[66:67]
	v_pk_fma_f32 v[72:73], v[26:27], v[64:65], v[72:73]
	v_pk_fma_f32 v[64:65], v[6:7], v[64:65], v[2:3]
	s_waitcnt vmcnt(13)
	v_lshlrev_b32_e32 v74, 16, v96
	v_and_b32_e32 v75, 0xffff0000, v96
	v_lshlrev_b32_e32 v54, 16, v97
	v_and_b32_e32 v55, 0xffff0000, v97
	v_lshlrev_b32_e32 v76, 16, v98
	v_and_b32_e32 v77, 0xffff0000, v98
	v_lshlrev_b32_e32 v56, 16, v99
	v_and_b32_e32 v57, 0xffff0000, v99
	v_pk_fma_f32 v[52:53], v[20:21], v[74:75], v[52:53]
	v_pk_fma_f32 v[50:51], v[22:23], v[54:55], v[50:51]
	v_pk_fma_f32 v[48:49], v[16:17], v[76:77], v[48:49]
	v_pk_fma_f32 v[86:87], v[18:19], v[56:57], v[46:47]
	v_cvt_pk_bf16_f32 v46, v52, v53
	v_cvt_pk_bf16_f32 v47, v50, v51
	v_cvt_pk_bf16_f32 v48, v48, v49
	v_cvt_pk_bf16_f32 v49, v86, v87
	global_store_dwordx4 v[60:61], v[46:49], off
	v_pk_fma_f32 v[60:61], v[12:13], v[82:83], v[8:9]
	v_pk_fma_f32 v[66:67], v[14:15], v[70:71], v[10:11]
	v_pk_fma_f32 v[70:71], v[4:5], v[84:85], v[0:1]
	v_pk_fma_f32 v[60:61], v[36:37], v[78:79], v[60:61]
	v_pk_fma_f32 v[66:67], v[38:39], v[62:63], v[66:67]
	v_pk_fma_f32 v[70:71], v[24:25], v[80:81], v[70:71]
	v_or_b32_e32 v50, 4, v40
	v_pk_fma_f32 v[60:61], v[32:33], v[74:75], v[60:61]
	v_pk_fma_f32 v[66:67], v[34:35], v[54:55], v[66:67]
	v_pk_fma_f32 v[70:71], v[28:29], v[76:77], v[70:71]
	v_pk_fma_f32 v[72:73], v[30:31], v[56:57], v[72:73]
	v_ashrrev_i32_e32 v51, 31, v50
	v_lshlrev_b64 v[52:53], 12, v[58:59]
	v_lshlrev_b64 v[58:59], 13, v[50:51]
	v_lshl_add_u64 v[52:53], v[42:43], 0, v[52:53]
	v_lshl_add_u64 v[58:59], v[44:45], 0, v[58:59]
	v_pk_fma_f32 v[62:63], v[14:15], v[62:63], v[10:11]
	v_pk_fma_f32 v[64:65], v[26:27], v[56:57], v[64:65]
	v_pk_fma_f32 v[62:63], v[38:39], v[54:55], v[62:63]
	v_lshlrev_b64 v[50:51], 12, v[50:51]
	v_lshl_add_u64 v[50:51], v[42:43], 0, v[50:51]
	v_pk_fma_f32 v[54:55], v[14:15], v[54:55], v[10:11]
	v_pk_fma_f32 v[56:57], v[6:7], v[56:57], v[2:3]
	s_waitcnt vmcnt(12)
	v_lshlrev_b32_e32 v82, 16, v100
	v_and_b32_e32 v83, 0xffff0000, v100
	v_lshlrev_b32_e32 v84, 16, v101
	v_and_b32_e32 v85, 0xffff0000, v101
	v_lshlrev_b32_e32 v86, 16, v102
	v_and_b32_e32 v87, 0xffff0000, v102
	v_lshlrev_b32_e32 v88, 16, v103
	v_and_b32_e32 v89, 0xffff0000, v103
	v_pk_fma_f32 v[46:47], v[20:21], v[82:83], v[60:61]
	v_pk_fma_f32 v[48:49], v[22:23], v[84:85], v[66:67]
	v_pk_fma_f32 v[60:61], v[16:17], v[86:87], v[70:71]
	v_pk_fma_f32 v[66:67], v[18:19], v[88:89], v[72:73]
	v_cvt_pk_bf16_f32 v46, v46, v47
	v_cvt_pk_bf16_f32 v47, v48, v49
	v_cvt_pk_bf16_f32 v48, v60, v61
	v_cvt_pk_bf16_f32 v49, v66, v67
	global_store_dwordx4 v[52:53], v[46:49], off
	v_pk_fma_f32 v[60:61], v[12:13], v[78:79], v[8:9]
	v_pk_fma_f32 v[66:67], v[4:5], v[80:81], v[0:1]
	v_pk_fma_f32 v[60:61], v[36:37], v[74:75], v[60:61]
	v_pk_fma_f32 v[66:67], v[24:25], v[76:77], v[66:67]
	v_or_b32_e32 v52, 5, v40
	v_pk_fma_f32 v[60:61], v[32:33], v[82:83], v[60:61]
	v_pk_fma_f32 v[62:63], v[34:35], v[84:85], v[62:63]
	v_pk_fma_f32 v[66:67], v[28:29], v[86:87], v[66:67]
	v_pk_fma_f32 v[64:65], v[30:31], v[88:89], v[64:65]
	v_ashrrev_i32_e32 v53, 31, v52
	v_lshlrev_b64 v[58:59], 13, v[52:53]
	v_lshl_add_u64 v[58:59], v[44:45], 0, v[58:59]
	v_pk_fma_f32 v[54:55], v[38:39], v[84:85], v[54:55]
	v_pk_fma_f32 v[56:57], v[26:27], v[88:89], v[56:57]
	v_lshlrev_b64 v[52:53], 12, v[52:53]
	v_lshl_add_u64 v[52:53], v[42:43], 0, v[52:53]
	s_waitcnt vmcnt(11)
	v_lshlrev_b32_e32 v70, 16, v104
	v_and_b32_e32 v71, 0xffff0000, v104
	v_lshlrev_b32_e32 v72, 16, v105
	v_and_b32_e32 v73, 0xffff0000, v105
	v_lshlrev_b32_e32 v78, 16, v106
	v_and_b32_e32 v79, 0xffff0000, v106
	v_lshlrev_b32_e32 v80, 16, v107
	v_and_b32_e32 v81, 0xffff0000, v107
	v_pk_fma_f32 v[46:47], v[20:21], v[70:71], v[60:61]
	v_pk_fma_f32 v[48:49], v[22:23], v[72:73], v[62:63]
	v_pk_fma_f32 v[60:61], v[16:17], v[78:79], v[66:67]
	v_pk_fma_f32 v[62:63], v[18:19], v[80:81], v[64:65]
	v_cvt_pk_bf16_f32 v46, v46, v47
	v_cvt_pk_bf16_f32 v47, v48, v49
	v_cvt_pk_bf16_f32 v48, v60, v61
	v_cvt_pk_bf16_f32 v49, v62, v63
	global_store_dwordx4 v[50:51], v[46:49], off
	v_pk_fma_f32 v[60:61], v[12:13], v[74:75], v[8:9]
	v_pk_fma_f32 v[62:63], v[4:5], v[76:77], v[0:1]
	v_pk_fma_f32 v[60:61], v[36:37], v[82:83], v[60:61]
	v_pk_fma_f32 v[62:63], v[24:25], v[86:87], v[62:63]
	v_or_b32_e32 v50, 6, v40
	v_pk_fma_f32 v[60:61], v[32:33], v[70:71], v[60:61]
	v_pk_fma_f32 v[54:55], v[34:35], v[72:73], v[54:55]
	v_pk_fma_f32 v[62:63], v[28:29], v[78:79], v[62:63]
	v_pk_fma_f32 v[56:57], v[30:31], v[80:81], v[56:57]
	v_ashrrev_i32_e32 v51, 31, v50
	v_lshlrev_b64 v[58:59], 13, v[50:51]
	v_lshl_add_u64 v[58:59], v[44:45], 0, v[58:59]
	v_lshlrev_b64 v[50:51], 12, v[50:51]
	v_lshl_add_u64 v[50:51], v[42:43], 0, v[50:51]
	s_waitcnt vmcnt(10)
	v_lshlrev_b32_e32 v64, 16, v108
	v_and_b32_e32 v65, 0xffff0000, v108
	v_lshlrev_b32_e32 v66, 16, v109
	v_and_b32_e32 v67, 0xffff0000, v109
	v_lshlrev_b32_e32 v74, 16, v110
	v_and_b32_e32 v75, 0xffff0000, v110
	v_lshlrev_b32_e32 v76, 16, v111
	v_and_b32_e32 v77, 0xffff0000, v111
	v_pk_fma_f32 v[46:47], v[20:21], v[64:65], v[60:61]
	v_pk_fma_f32 v[48:49], v[22:23], v[66:67], v[54:55]
	v_pk_fma_f32 v[54:55], v[16:17], v[74:75], v[62:63]
	v_pk_fma_f32 v[56:57], v[18:19], v[76:77], v[56:57]
	v_cvt_pk_bf16_f32 v46, v46, v47
	v_cvt_pk_bf16_f32 v47, v48, v49
	v_cvt_pk_bf16_f32 v48, v54, v55
	v_cvt_pk_bf16_f32 v49, v56, v57
	global_store_dwordx4 v[52:53], v[46:49], off
	v_pk_fma_f32 v[56:57], v[12:13], v[82:83], v[8:9]
	v_pk_fma_f32 v[58:59], v[14:15], v[84:85], v[10:11]
	v_pk_fma_f32 v[60:61], v[4:5], v[86:87], v[0:1]
	v_pk_fma_f32 v[62:63], v[6:7], v[88:89], v[2:3]
	v_pk_fma_f32 v[56:57], v[36:37], v[70:71], v[56:57]
	v_pk_fma_f32 v[58:59], v[38:39], v[72:73], v[58:59]
	v_pk_fma_f32 v[60:61], v[24:25], v[78:79], v[60:61]
	v_pk_fma_f32 v[62:63], v[26:27], v[80:81], v[62:63]
	v_or_b32_e32 v52, 7, v40
	v_pk_fma_f32 v[56:57], v[32:33], v[64:65], v[56:57]
	v_pk_fma_f32 v[58:59], v[34:35], v[66:67], v[58:59]
	v_pk_fma_f32 v[60:61], v[28:29], v[74:75], v[60:61]
	v_pk_fma_f32 v[62:63], v[30:31], v[76:77], v[62:63]
	v_ashrrev_i32_e32 v53, 31, v52
	v_lshlrev_b64 v[54:55], 13, v[52:53]
	v_lshl_add_u64 v[54:55], v[44:45], 0, v[54:55]
	v_lshlrev_b64 v[52:53], 12, v[52:53]
	v_lshl_add_u64 v[52:53], v[42:43], 0, v[52:53]
	s_waitcnt vmcnt(9)
	v_lshlrev_b32_e32 v82, 16, v112
	v_and_b32_e32 v83, 0xffff0000, v112
	v_lshlrev_b32_e32 v84, 16, v113
	v_and_b32_e32 v85, 0xffff0000, v113
	v_lshlrev_b32_e32 v86, 16, v114
	v_and_b32_e32 v87, 0xffff0000, v114
	v_lshlrev_b32_e32 v88, 16, v115
	v_and_b32_e32 v89, 0xffff0000, v115
	v_pk_fma_f32 v[46:47], v[20:21], v[82:83], v[56:57]
	v_pk_fma_f32 v[48:49], v[22:23], v[84:85], v[58:59]
	v_pk_fma_f32 v[56:57], v[16:17], v[86:87], v[60:61]
	v_pk_fma_f32 v[58:59], v[18:19], v[88:89], v[62:63]
	v_cvt_pk_bf16_f32 v46, v46, v47
	v_cvt_pk_bf16_f32 v47, v48, v49
	v_cvt_pk_bf16_f32 v48, v56, v57
	v_cvt_pk_bf16_f32 v49, v58, v59
	global_store_dwordx4 v[50:51], v[46:49], off
	v_pk_fma_f32 v[56:57], v[12:13], v[70:71], v[8:9]
	v_pk_fma_f32 v[58:59], v[14:15], v[72:73], v[10:11]
	v_pk_fma_f32 v[60:61], v[4:5], v[78:79], v[0:1]
	v_pk_fma_f32 v[62:63], v[6:7], v[80:81], v[2:3]
	v_pk_fma_f32 v[56:57], v[36:37], v[64:65], v[56:57]
	v_pk_fma_f32 v[58:59], v[38:39], v[66:67], v[58:59]
	v_pk_fma_f32 v[60:61], v[24:25], v[74:75], v[60:61]
	v_pk_fma_f32 v[62:63], v[26:27], v[76:77], v[62:63]
	v_or_b32_e32 v50, 8, v40
	v_pk_fma_f32 v[56:57], v[32:33], v[82:83], v[56:57]
	v_pk_fma_f32 v[58:59], v[34:35], v[84:85], v[58:59]
	v_pk_fma_f32 v[60:61], v[28:29], v[86:87], v[60:61]
	v_pk_fma_f32 v[62:63], v[30:31], v[88:89], v[62:63]
	v_ashrrev_i32_e32 v51, 31, v50
	v_lshlrev_b64 v[54:55], 13, v[50:51]
	v_lshl_add_u64 v[54:55], v[44:45], 0, v[54:55]
	v_lshlrev_b64 v[50:51], 12, v[50:51]
	v_lshl_add_u64 v[50:51], v[42:43], 0, v[50:51]
	s_waitcnt vmcnt(8)
	v_lshlrev_b32_e32 v70, 16, v116
	v_and_b32_e32 v71, 0xffff0000, v116
	v_lshlrev_b32_e32 v72, 16, v117
	v_and_b32_e32 v73, 0xffff0000, v117
	v_lshlrev_b32_e32 v78, 16, v118
	v_and_b32_e32 v79, 0xffff0000, v118
	v_lshlrev_b32_e32 v80, 16, v119
	v_and_b32_e32 v81, 0xffff0000, v119
	v_pk_fma_f32 v[46:47], v[20:21], v[70:71], v[56:57]
	v_pk_fma_f32 v[48:49], v[22:23], v[72:73], v[58:59]
	v_pk_fma_f32 v[56:57], v[16:17], v[78:79], v[60:61]
	v_pk_fma_f32 v[58:59], v[18:19], v[80:81], v[62:63]
	v_cvt_pk_bf16_f32 v46, v46, v47
	v_cvt_pk_bf16_f32 v47, v48, v49
	v_cvt_pk_bf16_f32 v48, v56, v57
	v_cvt_pk_bf16_f32 v49, v58, v59
	global_store_dwordx4 v[52:53], v[46:49], off
	v_pk_fma_f32 v[56:57], v[12:13], v[64:65], v[8:9]
	v_pk_fma_f32 v[58:59], v[14:15], v[66:67], v[10:11]
	v_pk_fma_f32 v[60:61], v[4:5], v[74:75], v[0:1]
	v_pk_fma_f32 v[62:63], v[6:7], v[76:77], v[2:3]
	v_pk_fma_f32 v[56:57], v[36:37], v[82:83], v[56:57]
	v_pk_fma_f32 v[58:59], v[38:39], v[84:85], v[58:59]
	v_pk_fma_f32 v[60:61], v[24:25], v[86:87], v[60:61]
	v_pk_fma_f32 v[62:63], v[26:27], v[88:89], v[62:63]
	v_or_b32_e32 v52, 9, v40
	v_pk_fma_f32 v[56:57], v[32:33], v[70:71], v[56:57]
	v_pk_fma_f32 v[58:59], v[34:35], v[72:73], v[58:59]
	v_pk_fma_f32 v[60:61], v[28:29], v[78:79], v[60:61]
	v_pk_fma_f32 v[62:63], v[30:31], v[80:81], v[62:63]
	v_ashrrev_i32_e32 v53, 31, v52
	v_lshlrev_b64 v[54:55], 13, v[52:53]
	v_lshl_add_u64 v[54:55], v[44:45], 0, v[54:55]
	v_lshlrev_b64 v[52:53], 12, v[52:53]
	v_lshl_add_u64 v[52:53], v[42:43], 0, v[52:53]
	s_waitcnt vmcnt(7)
	v_lshlrev_b32_e32 v64, 16, v120
	v_and_b32_e32 v65, 0xffff0000, v120
	v_lshlrev_b32_e32 v66, 16, v121
	v_and_b32_e32 v67, 0xffff0000, v121
	v_lshlrev_b32_e32 v74, 16, v122
	v_and_b32_e32 v75, 0xffff0000, v122
	v_lshlrev_b32_e32 v76, 16, v123
	v_and_b32_e32 v77, 0xffff0000, v123
	v_pk_fma_f32 v[46:47], v[20:21], v[64:65], v[56:57]
	v_pk_fma_f32 v[48:49], v[22:23], v[66:67], v[58:59]
	v_pk_fma_f32 v[56:57], v[16:17], v[74:75], v[60:61]
	v_pk_fma_f32 v[58:59], v[18:19], v[76:77], v[62:63]
	v_cvt_pk_bf16_f32 v46, v46, v47
	v_cvt_pk_bf16_f32 v47, v48, v49
	v_cvt_pk_bf16_f32 v48, v56, v57
	v_cvt_pk_bf16_f32 v49, v58, v59
	global_store_dwordx4 v[50:51], v[46:49], off
	v_pk_fma_f32 v[56:57], v[12:13], v[82:83], v[8:9]
	v_pk_fma_f32 v[58:59], v[14:15], v[84:85], v[10:11]
	v_pk_fma_f32 v[60:61], v[4:5], v[86:87], v[0:1]
	v_pk_fma_f32 v[62:63], v[6:7], v[88:89], v[2:3]
	v_pk_fma_f32 v[56:57], v[36:37], v[70:71], v[56:57]
	v_pk_fma_f32 v[58:59], v[38:39], v[72:73], v[58:59]
	v_pk_fma_f32 v[60:61], v[24:25], v[78:79], v[60:61]
	v_pk_fma_f32 v[62:63], v[26:27], v[80:81], v[62:63]
	v_or_b32_e32 v50, 10, v40
	v_pk_fma_f32 v[56:57], v[32:33], v[64:65], v[56:57]
	v_pk_fma_f32 v[58:59], v[34:35], v[66:67], v[58:59]
	v_pk_fma_f32 v[60:61], v[28:29], v[74:75], v[60:61]
	v_pk_fma_f32 v[62:63], v[30:31], v[76:77], v[62:63]
	v_ashrrev_i32_e32 v51, 31, v50
	v_lshlrev_b64 v[54:55], 13, v[50:51]
	v_lshl_add_u64 v[54:55], v[44:45], 0, v[54:55]
	v_lshlrev_b64 v[50:51], 12, v[50:51]
	v_lshl_add_u64 v[50:51], v[42:43], 0, v[50:51]
	s_waitcnt vmcnt(6)
	v_lshlrev_b32_e32 v82, 16, v124
	v_and_b32_e32 v83, 0xffff0000, v124
	v_lshlrev_b32_e32 v84, 16, v125
	v_and_b32_e32 v85, 0xffff0000, v125
	v_lshlrev_b32_e32 v86, 16, v126
	v_and_b32_e32 v87, 0xffff0000, v126
	v_lshlrev_b32_e32 v88, 16, v127
	v_and_b32_e32 v89, 0xffff0000, v127
	v_pk_fma_f32 v[46:47], v[20:21], v[82:83], v[56:57]
	v_pk_fma_f32 v[48:49], v[22:23], v[84:85], v[58:59]
	v_pk_fma_f32 v[56:57], v[16:17], v[86:87], v[60:61]
	v_pk_fma_f32 v[58:59], v[18:19], v[88:89], v[62:63]
	v_cvt_pk_bf16_f32 v46, v46, v47
	v_cvt_pk_bf16_f32 v47, v48, v49
	v_cvt_pk_bf16_f32 v48, v56, v57
	v_cvt_pk_bf16_f32 v49, v58, v59
	global_store_dwordx4 v[52:53], v[46:49], off
	v_pk_fma_f32 v[56:57], v[12:13], v[70:71], v[8:9]
	v_pk_fma_f32 v[58:59], v[14:15], v[72:73], v[10:11]
	v_pk_fma_f32 v[60:61], v[4:5], v[78:79], v[0:1]
	v_pk_fma_f32 v[62:63], v[6:7], v[80:81], v[2:3]
	v_pk_fma_f32 v[56:57], v[36:37], v[64:65], v[56:57]
	v_pk_fma_f32 v[58:59], v[38:39], v[66:67], v[58:59]
	v_pk_fma_f32 v[60:61], v[24:25], v[74:75], v[60:61]
	v_pk_fma_f32 v[62:63], v[26:27], v[76:77], v[62:63]
	v_or_b32_e32 v52, 11, v40
	v_pk_fma_f32 v[56:57], v[32:33], v[82:83], v[56:57]
	v_pk_fma_f32 v[58:59], v[34:35], v[84:85], v[58:59]
	v_pk_fma_f32 v[60:61], v[28:29], v[86:87], v[60:61]
	v_pk_fma_f32 v[62:63], v[30:31], v[88:89], v[62:63]
	v_ashrrev_i32_e32 v53, 31, v52
	v_lshlrev_b64 v[54:55], 13, v[52:53]
	v_lshl_add_u64 v[54:55], v[44:45], 0, v[54:55]
	s_waitcnt vmcnt(5)
	v_lshlrev_b32_e32 v70, 16, v136
	v_and_b32_e32 v71, 0xffff0000, v136
	v_lshlrev_b32_e32 v72, 16, v137
	v_and_b32_e32 v73, 0xffff0000, v137
	v_lshlrev_b32_e32 v78, 16, v138
	v_and_b32_e32 v79, 0xffff0000, v138
	v_lshlrev_b32_e32 v80, 16, v139
	v_and_b32_e32 v81, 0xffff0000, v139
	v_pk_fma_f32 v[46:47], v[20:21], v[70:71], v[56:57]
	v_pk_fma_f32 v[48:49], v[22:23], v[72:73], v[58:59]
	v_pk_fma_f32 v[56:57], v[16:17], v[78:79], v[60:61]
	v_pk_fma_f32 v[58:59], v[18:19], v[80:81], v[62:63]
	v_cvt_pk_bf16_f32 v46, v46, v47
	v_cvt_pk_bf16_f32 v47, v48, v49
	v_cvt_pk_bf16_f32 v48, v56, v57
	v_cvt_pk_bf16_f32 v49, v58, v59
	global_store_dwordx4 v[50:51], v[46:49], off
	v_pk_fma_f32 v[56:57], v[12:13], v[64:65], v[8:9]
	v_pk_fma_f32 v[58:59], v[14:15], v[66:67], v[10:11]
	v_pk_fma_f32 v[60:61], v[4:5], v[74:75], v[0:1]
	v_pk_fma_f32 v[62:63], v[6:7], v[76:77], v[2:3]
	v_pk_fma_f32 v[56:57], v[36:37], v[82:83], v[56:57]
	v_pk_fma_f32 v[58:59], v[38:39], v[84:85], v[58:59]
	v_pk_fma_f32 v[60:61], v[24:25], v[86:87], v[60:61]
	v_pk_fma_f32 v[62:63], v[26:27], v[88:89], v[62:63]
	v_or_b32_e32 v54, 12, v40
	v_pk_fma_f32 v[56:57], v[32:33], v[70:71], v[56:57]
	v_pk_fma_f32 v[58:59], v[34:35], v[72:73], v[58:59]
	v_pk_fma_f32 v[60:61], v[28:29], v[78:79], v[60:61]
	v_pk_fma_f32 v[62:63], v[30:31], v[80:81], v[62:63]
	v_ashrrev_i32_e32 v55, 31, v54
	v_lshlrev_b64 v[50:51], 12, v[52:53]
	v_lshlrev_b64 v[52:53], 13, v[54:55]
	v_lshl_add_u64 v[50:51], v[42:43], 0, v[50:51]
	v_lshl_add_u64 v[52:53], v[44:45], 0, v[52:53]
	s_waitcnt vmcnt(4)
	v_lshlrev_b32_e32 v64, 16, v144
	v_and_b32_e32 v65, 0xffff0000, v144
	v_lshlrev_b32_e32 v66, 16, v145
	v_and_b32_e32 v67, 0xffff0000, v145
	v_lshlrev_b32_e32 v74, 16, v146
	v_and_b32_e32 v75, 0xffff0000, v146
	v_lshlrev_b32_e32 v76, 16, v147
	v_and_b32_e32 v77, 0xffff0000, v147
	v_pk_fma_f32 v[46:47], v[20:21], v[64:65], v[56:57]
	v_pk_fma_f32 v[48:49], v[22:23], v[66:67], v[58:59]
	v_pk_fma_f32 v[56:57], v[16:17], v[74:75], v[60:61]
	v_pk_fma_f32 v[58:59], v[18:19], v[76:77], v[62:63]
	v_cvt_pk_bf16_f32 v46, v46, v47
	v_cvt_pk_bf16_f32 v47, v48, v49
	v_cvt_pk_bf16_f32 v48, v56, v57
	v_cvt_pk_bf16_f32 v49, v58, v59
	global_store_dwordx4 v[50:51], v[46:49], off
	v_or_b32_e32 v58, 13, v40
	v_ashrrev_i32_e32 v59, 31, v58
	v_lshlrev_b64 v[46:47], 12, v[54:55]
	v_lshlrev_b64 v[48:49], 13, v[58:59]
	v_lshl_add_u64 v[60:61], v[42:43], 0, v[46:47]
	v_lshl_add_u64 v[62:63], v[44:45], 0, v[48:49]
	v_pk_fma_f32 v[46:47], v[12:13], v[82:83], v[8:9]
	v_pk_fma_f32 v[48:49], v[14:15], v[84:85], v[10:11]
	v_pk_fma_f32 v[54:55], v[4:5], v[86:87], v[0:1]
	v_pk_fma_f32 v[56:57], v[6:7], v[88:89], v[2:3]
	v_pk_fma_f32 v[46:47], v[36:37], v[70:71], v[46:47]
	v_pk_fma_f32 v[48:49], v[38:39], v[72:73], v[48:49]
	v_pk_fma_f32 v[54:55], v[24:25], v[78:79], v[54:55]
	v_pk_fma_f32 v[56:57], v[26:27], v[80:81], v[56:57]
	v_pk_fma_f32 v[82:83], v[32:33], v[64:65], v[46:47]
	v_pk_fma_f32 v[84:85], v[34:35], v[66:67], v[48:49]
	v_pk_fma_f32 v[54:55], v[28:29], v[74:75], v[54:55]
	v_pk_fma_f32 v[56:57], v[30:31], v[76:77], v[56:57]
	v_or_b32_e32 v40, 14, v40
	v_ashrrev_i32_e32 v41, 31, v40
	v_lshlrev_b64 v[58:59], 12, v[58:59]
	v_lshl_add_u64 v[58:59], v[42:43], 0, v[58:59]
	s_waitcnt vmcnt(3)
	v_lshlrev_b32_e32 v46, 16, v148
	v_and_b32_e32 v47, 0xffff0000, v148
	v_lshlrev_b32_e32 v48, 16, v149
	v_and_b32_e32 v49, 0xffff0000, v149
	v_lshlrev_b32_e32 v50, 16, v150
	v_and_b32_e32 v51, 0xffff0000, v150
	v_lshlrev_b32_e32 v52, 16, v151
	v_and_b32_e32 v53, 0xffff0000, v151
	v_pk_fma_f32 v[82:83], v[20:21], v[46:47], v[82:83]
	v_pk_fma_f32 v[84:85], v[22:23], v[48:49], v[84:85]
	v_pk_fma_f32 v[86:87], v[16:17], v[50:51], v[54:55]
	v_pk_fma_f32 v[88:89], v[18:19], v[52:53], v[56:57]
	v_cvt_pk_bf16_f32 v54, v82, v83
	v_cvt_pk_bf16_f32 v55, v84, v85
	v_cvt_pk_bf16_f32 v56, v86, v87
	v_cvt_pk_bf16_f32 v57, v88, v89
	global_store_dwordx4 v[60:61], v[54:57], off
	v_pk_fma_f32 v[62:63], v[12:13], v[70:71], v[8:9]
	v_pk_fma_f32 v[70:71], v[14:15], v[72:73], v[10:11]
	v_pk_fma_f32 v[72:73], v[4:5], v[78:79], v[0:1]
	v_pk_fma_f32 v[78:79], v[6:7], v[80:81], v[2:3]
	v_pk_fma_f32 v[62:63], v[36:37], v[64:65], v[62:63]
	v_pk_fma_f32 v[70:71], v[38:39], v[66:67], v[70:71]
	v_pk_fma_f32 v[72:73], v[24:25], v[74:75], v[72:73]
	v_pk_fma_f32 v[78:79], v[26:27], v[76:77], v[78:79]
	v_pk_fma_f32 v[62:63], v[32:33], v[46:47], v[62:63]
	v_pk_fma_f32 v[70:71], v[34:35], v[48:49], v[70:71]
	v_pk_fma_f32 v[72:73], v[28:29], v[50:51], v[72:73]
	v_pk_fma_f32 v[78:79], v[30:31], v[52:53], v[78:79]
	v_lshlrev_b64 v[60:61], 13, v[40:41]
	v_lshl_add_u64 v[60:61], v[44:45], 0, v[60:61]
	v_lshlrev_b64 v[40:41], 12, v[40:41]
	v_lshl_add_u64 v[40:41], v[42:43], 0, v[40:41]
	s_waitcnt vmcnt(2)
	v_lshlrev_b32_e32 v80, 16, v152
	v_and_b32_e32 v81, 0xffff0000, v152
	v_lshlrev_b32_e32 v82, 16, v153
	v_and_b32_e32 v83, 0xffff0000, v153
	v_lshlrev_b32_e32 v84, 16, v154
	v_and_b32_e32 v85, 0xffff0000, v154
	v_lshlrev_b32_e32 v86, 16, v155
	v_and_b32_e32 v87, 0xffff0000, v155
	v_pk_fma_f32 v[54:55], v[20:21], v[80:81], v[62:63]
	v_pk_fma_f32 v[56:57], v[22:23], v[82:83], v[70:71]
	v_pk_fma_f32 v[62:63], v[16:17], v[84:85], v[72:73]
	v_pk_fma_f32 v[70:71], v[18:19], v[86:87], v[78:79]
	v_cvt_pk_bf16_f32 v54, v54, v55
	v_cvt_pk_bf16_f32 v55, v56, v57
	v_cvt_pk_bf16_f32 v56, v62, v63
	v_cvt_pk_bf16_f32 v57, v70, v71
	global_store_dwordx4 v[58:59], v[54:57], off
	v_or_b32_e32 v58, 15, v68
	v_ashrrev_i32_e32 v59, 31, v58
	v_lshlrev_b64 v[60:61], 13, v[58:59]
	v_lshl_add_u64 v[44:45], v[44:45], 0, v[60:61]
	v_pk_fma_f32 v[60:61], v[12:13], v[64:65], v[8:9]
	v_pk_fma_f32 v[62:63], v[14:15], v[66:67], v[10:11]
	v_pk_fma_f32 v[64:65], v[4:5], v[74:75], v[0:1]
	v_pk_fma_f32 v[66:67], v[6:7], v[76:77], v[2:3]
	v_pk_fma_f32 v[60:61], v[36:37], v[46:47], v[60:61]
	v_pk_fma_f32 v[62:63], v[38:39], v[48:49], v[62:63]
	v_pk_fma_f32 v[64:65], v[24:25], v[50:51], v[64:65]
	v_pk_fma_f32 v[66:67], v[26:27], v[52:53], v[66:67]
	v_pk_fma_f32 v[60:61], v[32:33], v[80:81], v[60:61]
	v_pk_fma_f32 v[62:63], v[34:35], v[82:83], v[62:63]
	v_pk_fma_f32 v[64:65], v[28:29], v[84:85], v[64:65]
	v_pk_fma_f32 v[66:67], v[30:31], v[86:87], v[66:67]
	v_pk_fma_f32 v[8:9], v[12:13], v[46:47], v[8:9]
	v_pk_fma_f32 v[10:11], v[14:15], v[48:49], v[10:11]
	v_pk_fma_f32 v[0:1], v[4:5], v[50:51], v[0:1]
	v_pk_fma_f32 v[2:3], v[6:7], v[52:53], v[2:3]
	v_pk_fma_f32 v[4:5], v[36:37], v[80:81], v[8:9]
	v_pk_fma_f32 v[6:7], v[38:39], v[82:83], v[10:11]
	v_pk_fma_f32 v[0:1], v[24:25], v[84:85], v[0:1]
	v_pk_fma_f32 v[2:3], v[26:27], v[86:87], v[2:3]
	s_waitcnt vmcnt(1)
	v_lshlrev_b32_e32 v68, 16, v156
	v_and_b32_e32 v69, 0xffff0000, v156
	v_lshlrev_b32_e32 v70, 16, v157
	v_and_b32_e32 v71, 0xffff0000, v157
	v_lshlrev_b32_e32 v72, 16, v158
	v_and_b32_e32 v73, 0xffff0000, v158
	v_lshlrev_b32_e32 v74, 16, v159
	v_and_b32_e32 v75, 0xffff0000, v159
	v_pk_fma_f32 v[54:55], v[20:21], v[68:69], v[60:61]
	v_pk_fma_f32 v[56:57], v[22:23], v[70:71], v[62:63]
	v_pk_fma_f32 v[60:61], v[16:17], v[72:73], v[64:65]
	v_pk_fma_f32 v[62:63], v[18:19], v[74:75], v[66:67]
	v_cvt_pk_bf16_f32 v54, v54, v55
	v_cvt_pk_bf16_f32 v55, v56, v57
	v_cvt_pk_bf16_f32 v56, v60, v61
	v_cvt_pk_bf16_f32 v57, v62, v63
	global_store_dwordx4 v[40:41], v[54:57], off
	v_pk_fma_f32 v[4:5], v[32:33], v[68:69], v[4:5]
	v_pk_fma_f32 v[6:7], v[34:35], v[70:71], v[6:7]
	v_pk_fma_f32 v[0:1], v[28:29], v[72:73], v[0:1]
	v_pk_fma_f32 v[2:3], v[30:31], v[74:75], v[2:3]
	v_lshlrev_b64 v[44:45], 12, v[58:59]
	v_lshl_add_u64 v[42:43], v[42:43], 0, v[44:45]
	v_mov_b32_e32 v40, v236
	v_mov_b32_e32 v41, 1
	s_waitcnt vmcnt(0)
	v_lshlrev_b32_e32 v8, 16, v160
	v_and_b32_e32 v9, 0xffff0000, v160
	v_lshlrev_b32_e32 v10, 16, v161
	v_and_b32_e32 v11, 0xffff0000, v161
	v_lshlrev_b32_e32 v12, 16, v162
	v_and_b32_e32 v13, 0xffff0000, v162
	v_lshlrev_b32_e32 v14, 16, v163
	v_and_b32_e32 v15, 0xffff0000, v163
	v_pk_fma_f32 v[4:5], v[20:21], v[8:9], v[4:5]
	v_pk_fma_f32 v[6:7], v[22:23], v[10:11], v[6:7]
	v_pk_fma_f32 v[8:9], v[16:17], v[12:13], v[0:1]
	v_pk_fma_f32 v[10:11], v[18:19], v[14:15], v[2:3]
	v_cvt_pk_bf16_f32 v0, v4, v5
	v_cvt_pk_bf16_f32 v1, v6, v7
	v_cvt_pk_bf16_f32 v2, v8, v9
	v_cvt_pk_bf16_f32 v3, v10, v11
	global_store_dwordx4 v[42:43], v[0:3], off
	s_waitcnt vmcnt(0)
	s_barrier
	s_ashr_i32 s35, s34, 31
	v_bfe_i32 v2, v40, 27, 1
	v_lshlrev_b32_e32 v0, 4, v40
	v_lshrrev_b32_e32 v2, 22, v2
	v_add_u32_e32 v3, 0x2000, v0
	v_add_u32_e32 v2, v0, v2
	v_ashrrev_i32_e32 v4, 31, v3
	v_and_b32_e32 v2, 0xfffffc00, v2
	v_lshrrev_b32_e32 v4, 22, v4
	v_sub_u32_e32 v0, v0, v2
	v_ashrrev_i32_e32 v1, 31, v40
	v_add_u32_e32 v4, v3, v4
	v_lshrrev_b32_e32 v5, 4, v0
	v_lshrrev_b32_e32 v1, 26, v1
	v_ashrrev_i32_e32 v4, 10, v4
	v_bitop3_b32 v0, v5, v0, 32 bitop3:0x6c
	v_add_u32_e32 v1, v40, v1
	v_mul_i32_i24_e32 v5, 0x400, v4
	v_lshlrev_b32_e32 v6, 3, v4
	v_ashrrev_i32_e32 v7, 31, v0
	v_ashrrev_i32_e32 v1, 6, v1
	v_sub_u32_e32 v3, v3, v5
	v_and_b32_e32 v5, -16, v6
	v_lshrrev_b32_e32 v6, 26, v7
	v_lshlrev_b32_e32 v2, 3, v1
	v_lshrrev_b32_e32 v7, 4, v3
	v_add_u32_e32 v6, v0, v6
	v_readfirstlane_b32 s3, v40
	v_and_b32_e32 v2, -16, v2
	v_bitop3_b32 v3, v7, v3, 32 bitop3:0x6c
	v_ashrrev_i32_e32 v7, 6, v6
	v_and_b32_e32 v6, 0xc0, v6
	s_lshl_b32 s6, s36, 9
	s_ashr_i32 s37, s36, 31
	s_ashr_i32 s16, s3, 6
	v_ashrrev_i32_e32 v8, 31, v3
	v_add_u32_e32 v2, v7, v2
	v_sub_u32_e32 v0, v0, v6
	s_ashr_i32 s7, s3, 8
	s_lshl_b64 s[4:5], s[34:35], 20
	s_and_b32 s15, s6, 0xe00
	s_lshl_b64 s[8:9], s[36:37], 17
	s_lshl_b32 s6, s16, 10
	v_lshlrev_b32_e32 v1, 5, v1
	v_and_b32_e32 v6, 3, v7
	v_lshrrev_b32_e32 v7, 26, v8
	v_ashrrev_i16_sdwa v0, v41, sext(v0) dst_sel:DWORD dst_unused:UNUSED_PAD src0_sel:DWORD src1_sel:BYTE_0
	v_lshlrev_b32_e32 v8, 1, v2
	v_lshrrev_b32_e32 v9, 2, v2
	s_add_u32 s8, s10, s8
	v_and_b32_e32 v1, 32, v1
	v_and_or_b32 v6, v2, s14, v6
	v_add_u32_e32 v7, v3, v7
	v_bfe_i32 v0, v0, 0, 16
	v_and_b32_e32 v8, 24, v8
	v_and_b32_e32 v9, 4, v9
	s_addc_u32 s9, s11, s9
	s_add_i32 s13, s6, 0
	v_ashrrev_i32_e32 v10, 6, v7
	v_and_b32_e32 v7, 0xc0, v7
	v_or3_b32 v6, v6, v9, v8
	v_add_lshl_u32 v0, v1, v0, 1
	s_add_i32 m0, s13, 0x10000
	v_add_u32_e32 v1, v10, v5
	v_sub_u32_e32 v3, v3, v7
	v_lshl_add_u32 v128, v6, 9, v0
	v_lshlrev_b32_e32 v4, 5, v4
	v_and_b32_e32 v5, 3, v10
	v_lshl_add_u32 v130, v2, 12, v0
	v_ashrrev_i16_sdwa v0, v41, sext(v3) dst_sel:DWORD dst_unused:UNUSED_PAD src0_sel:DWORD src1_sel:BYTE_0
	v_lshlrev_b32_e32 v2, 1, v1
	v_lshrrev_b32_e32 v3, 2, v1
	global_load_lds_dwordx4 v128, s[8:9]
	s_add_i32 m0, s13, 0x12000
	v_and_b32_e32 v4, 32, v4
	v_and_or_b32 v5, v1, s14, v5
	v_bfe_i32 v0, v0, 0, 16
	v_and_b32_e32 v2, 24, v2
	v_and_b32_e32 v3, 4, v3
	s_add_u32 s14, s0, s4
	v_or3_b32 v2, v5, v3, v2
	v_add_lshl_u32 v0, v4, v0, 1
	s_addc_u32 s17, s1, s5
	v_lshl_add_u32 v134, v2, 9, v0
	s_add_u32 s4, s8, 0x10000
	global_load_lds_dwordx4 v134, s[8:9]
	s_addc_u32 s5, s9, 0
	s_add_i32 m0, s13, 0x14000
	v_lshl_add_u32 v132, v1, 12, v0
	global_load_lds_dwordx4 v128, s[4:5]
	s_add_i32 m0, s13, 0x16000
	s_add_u32 s38, s14, s15
	s_addc_u32 s39, s17, 0
	s_add_i32 s35, s13, 0x2000
	global_load_lds_dwordx4 v134, s[4:5]
	s_mov_b32 m0, s13
	s_add_u32 s4, s38, 0x80000
	global_load_lds_dwordx4 v130, s[38:39]
	s_mov_b32 m0, s35
	s_addc_u32 s5, s39, 0
	s_add_i32 s37, s13, 0x4000
	global_load_lds_dwordx4 v132, s[38:39]
	s_add_i32 s44, s13, 0x6000
	s_mov_b32 m0, s37
	s_cmp_eq_u32 s7, 1
	global_load_lds_dwordx4 v130, s[4:5]
	s_mov_b32 m0, s44
	v_lshl_add_u64 v[6:7], s[8:9], 0, v[128:129]
	global_load_lds_dwordx4 v132, s[4:5]
	v_lshl_add_u64 v[4:5], s[8:9], 0, v[134:135]
	v_lshl_add_u64 v[0:1], s[38:39], 0, v[130:131]
	s_cselect_b64 s[4:5], -1, 0
	s_cmp_lg_u32 s7, 1
	v_lshl_add_u64 v[2:3], s[38:39], 0, v[132:133]
	s_cbranch_scc1 .LBB0_652
	s_barrier
